# HGRN2: next-chunk loads issued at the top of the chunk (a full chunk ahead), log-f reloaded in place after the cumsum, q/k/v through spare registers; rec in-proj epilogue: eight ssq loads issued toget
# baseline (speedup 1.0000x reference)
.LBB0_411:
	s_lshl_b32 s0, s3, 8
	s_add_i32 s0, s0, s79
	v_mbcnt_lo_u32_b32 v130, -1, 0
	v_mbcnt_hi_u32_b32 v130, -1, v130
	v_cndmask_b32_e64 v131, 0, 1, s[18:19]
	v_and_or_b32 v150, v130, 15, s0
	v_ashrrev_i32_e32 v151, 31, v150
	v_cmp_ne_u32_e64 s[90:91], 1, v131
	s_andn2_b64 vcc, exec, s[18:19]
	v_lshl_add_u64 v[152:153], v[150:151], 2, s[8:9]
	s_movk_i32 s28, 0x6000
	s_cbranch_vccnz .LBB0_413
	global_load_dword v228, v[152:153], off
	global_load_dword v229, v[152:153], off offset:64
	global_load_dword v230, v[152:153], off offset:128
	global_load_dword v231, v[152:153], off offset:192
	global_load_dword v232, v[152:153], off offset:512
	global_load_dword v233, v[152:153], off offset:576
	global_load_dword v234, v[152:153], off offset:640
	global_load_dword v235, v[152:153], off offset:704
	s_waitcnt vmcnt(0)
	v_mov_b32_e32 v131, v228
	v_fmamk_f32 v131, v131, 0x3a000000, v197
	v_mul_f32_e32 v132, 0x4b800000, v131
	v_cmp_gt_f32_e32 vcc, s81, v131
	s_nop 1
	v_cndmask_b32_e32 v131, v131, v132, vcc
	v_rsq_f32_e32 v131, v131
	s_nop 0
	v_mul_f32_e32 v132, 0x45800000, v131
	v_cndmask_b32_e32 v158, v131, v132, vcc
	s_branch .LBB0_414

.LBB0_427:
	v_mov_b32_e32 v114, v229
	v_fmamk_f32 v114, v114, 0x3a000000, v197
	v_mul_f32_e32 v115, 0x4b800000, v114
	v_cmp_gt_f32_e32 vcc, s81, v114
	s_nop 1
	v_cndmask_b32_e32 v114, v114, v115, vcc
	v_rsq_f32_e32 v114, v114
	s_nop 0
	v_mul_f32_e32 v115, 0x45800000, v114
	v_cndmask_b32_e32 v126, v114, v115, vcc
	s_branch .LBB0_437

.LBB0_450:
	v_mov_b32_e32 v98, v230
	v_fmamk_f32 v98, v98, 0x3a000000, v197
	v_mul_f32_e32 v99, 0x4b800000, v98
	v_cmp_gt_f32_e32 vcc, s81, v98
	s_nop 1
	v_cndmask_b32_e32 v98, v98, v99, vcc
	v_rsq_f32_e32 v98, v98
	s_nop 0
	v_mul_f32_e32 v99, 0x45800000, v98
	v_cndmask_b32_e32 v110, v98, v99, vcc
	s_branch .LBB0_460

.LBB0_473:
	v_mov_b32_e32 v82, v231
	v_fmamk_f32 v82, v82, 0x3a000000, v197
	v_mul_f32_e32 v83, 0x4b800000, v82
	v_cmp_gt_f32_e32 vcc, s81, v82
	s_nop 1
	v_cndmask_b32_e32 v82, v82, v83, vcc
	v_rsq_f32_e32 v82, v82
	s_nop 0
	v_mul_f32_e32 v83, 0x45800000, v82
	v_cndmask_b32_e32 v94, v82, v83, vcc
	s_branch .LBB0_483

.LBB0_496:
	v_mov_b32_e32 v66, v232
	v_fmamk_f32 v66, v66, 0x3a000000, v197
	v_mul_f32_e32 v67, 0x4b800000, v66
	v_cmp_gt_f32_e32 vcc, s81, v66
	s_nop 1
	v_cndmask_b32_e32 v66, v66, v67, vcc
	v_rsq_f32_e32 v66, v66
	s_nop 0
	v_mul_f32_e32 v67, 0x45800000, v66
	v_cndmask_b32_e32 v78, v66, v67, vcc
	s_branch .LBB0_506

.LBB0_519:
	v_mov_b32_e32 v50, v233
	v_fmamk_f32 v50, v50, 0x3a000000, v197
	v_mul_f32_e32 v51, 0x4b800000, v50
	v_cmp_gt_f32_e32 vcc, s81, v50
	s_nop 1
	v_cndmask_b32_e32 v50, v50, v51, vcc
	v_rsq_f32_e32 v50, v50
	s_nop 0
	v_mul_f32_e32 v51, 0x45800000, v50
	v_cndmask_b32_e32 v62, v50, v51, vcc
	s_branch .LBB0_529

.LBB0_542:
	v_mov_b32_e32 v34, v234
	v_fmamk_f32 v34, v34, 0x3a000000, v197
	v_mul_f32_e32 v35, 0x4b800000, v34
	v_cmp_gt_f32_e32 vcc, s81, v34
	s_nop 1
	v_cndmask_b32_e32 v34, v34, v35, vcc
	v_rsq_f32_e32 v34, v34
	s_nop 0
	v_mul_f32_e32 v35, 0x45800000, v34
	v_cndmask_b32_e32 v46, v34, v35, vcc
	s_branch .LBB0_552

.LBB0_565:
	v_mov_b32_e32 v18, v235
	v_fmamk_f32 v18, v18, 0x3a000000, v197
	v_mul_f32_e32 v19, 0x4b800000, v18
	v_cmp_gt_f32_e32 vcc, s81, v18
	s_nop 1
	v_cndmask_b32_e32 v18, v18, v19, vcc
	v_rsq_f32_e32 v18, v18
	s_nop 0
	v_mul_f32_e32 v19, 0x45800000, v18
	v_cndmask_b32_e32 v30, v18, v19, vcc
	s_branch .LBB0_575

.LBB0_1167:
	s_or_b64 exec, exec, s[0:1]
	s_lshl_b32 s36, s72, 7
	s_ashr_i32 s1, s3, 31
	v_readlane_b32 s0, v251, 10
	s_add_u32 s0, s0, s3
	v_readlane_b32 s3, v251, 11
	s_addc_u32 s1, s3, s1
	s_ashr_i32 s3, s2, 31
	s_lshl_b64 s[6:7], s[36:37], 2
	s_waitcnt lgkmcnt(0)
	s_add_u32 s6, s4, s6
	s_addc_u32 s7, s5, s7
	s_ashr_i32 s5, s8, 31
	s_add_u32 s4, s30, s8
	s_addc_u32 s5, s31, s5
	v_readlane_b32 s8, v254, 15
	s_add_u32 s2, s8, s2
	v_readlane_b32 s8, v254, 16
	v_lshlrev_b32_e32 v74, 1, v18
	s_addc_u32 s3, s8, s3
	v_ashrrev_i32_e32 v75, 31, v74
	v_lshl_add_u64 v[76:77], v[74:75], 2, s[2:3]
	v_readlane_b32 s2, v254, 39
	s_add_u32 s2, s0, s2
	v_readlane_b32 s3, v254, 38
	v_readlane_b32 s8, v254, 14
	s_addc_u32 s3, s1, s3
	s_lshl_b32 s36, s8, 1
	s_add_u32 s2, s2, s36
	s_addc_u32 s3, s3, 0
	v_lshl_add_u64 v[2:3], v[74:75], 1, s[2:3]
	s_mov_b64 s[2:3], 0x2000
	v_lshl_add_u64 v[78:79], v[2:3], 0, s[2:3]
	v_readlane_b32 s2, v254, 42
	v_mov_b64_e32 v[4:5], s[0:1]
	s_movk_i32 s11, 0x4000
	v_add_u32_e32 v6, s2, v18
	v_mad_i64_i32 v[4:5], s[2:3], v6, s28, v[4:5]
	v_add_co_u32_e32 v6, vcc, s66, v2
	s_movk_i32 s3, 0x2000
	s_nop 0
	v_addc_co_u32_e32 v7, vcc, 0, v3, vcc
	v_add_co_u32_e32 v8, vcc, s3, v76
	s_mov_b32 s3, 0x9000
	s_nop 0
	v_addc_co_u32_e32 v9, vcc, 0, v77, vcc
	v_add_co_u32_e32 v10, vcc, s3, v2
	s_mov_b32 s3, 0xf000
	s_nop 0
	v_addc_co_u32_e32 v11, vcc, 0, v3, vcc
	v_add_co_u32_e32 v12, vcc, s11, v76
	v_readlane_b32 s10, v254, 17
	s_nop 0
	v_addc_co_u32_e32 v13, vcc, 0, v77, vcc
	v_add_co_u32_e32 v14, vcc, s3, v2
	s_mov_b32 s3, 0x15000
	s_nop 0
	v_addc_co_u32_e32 v15, vcc, 0, v3, vcc
	v_add_co_u32_e32 v16, vcc, s28, v76
	s_lshl_b32 s8, s10, 1
	s_nop 0
	v_addc_co_u32_e32 v17, vcc, 0, v77, vcc
	v_add_co_u32_e32 v20, vcc, s3, v2
	s_mov_b32 s3, 0x8000
	s_nop 0
	v_addc_co_u32_e32 v21, vcc, 0, v3, vcc
	global_load_dword v75, v[6:7], off offset:-4096
	global_load_dword v125, v[6:7], off
	global_load_dword v126, v[10:11], off offset:-4096
	global_load_dword v127, v[10:11], off
	global_load_dword v128, v[14:15], off offset:-4096
	global_load_dword v129, v[14:15], off
	global_load_dword v130, v[20:21], off offset:-4096
	global_load_dword v131, v[20:21], off
	v_add_co_u32_e32 v6, vcc, s3, v76
	s_mov_b32 s3, 0x1b000
	s_nop 0
	v_addc_co_u32_e32 v7, vcc, 0, v77, vcc
	global_load_dwordx2 v[80:81], v[8:9], off
	global_load_dwordx2 v[82:83], v[12:13], off
	global_load_dwordx2 v[86:87], v[16:17], off
	global_load_dwordx2 v[90:91], v[6:7], off
	v_add_co_u32_e32 v6, vcc, s3, v2
	s_mov_b32 s3, 0xa000
	s_nop 0
	v_addc_co_u32_e32 v7, vcc, 0, v3, vcc
	v_add_co_u32_e32 v8, vcc, s3, v76
	s_mov_b32 s3, 0x21000
	s_nop 0
	v_addc_co_u32_e32 v9, vcc, 0, v77, vcc
	v_add_co_u32_e32 v10, vcc, s3, v2
	s_mov_b32 s3, 0xc000
	s_nop 0
	v_addc_co_u32_e32 v11, vcc, 0, v3, vcc
	v_add_co_u32_e32 v12, vcc, s3, v76
	s_mov_b32 s3, 0x27000
	s_nop 0
	v_addc_co_u32_e32 v13, vcc, 0, v77, vcc
	v_add_co_u32_e32 v14, vcc, s3, v2
	s_mov_b32 s3, 0xe000
	s_nop 0
	v_addc_co_u32_e32 v15, vcc, 0, v3, vcc
	v_add_co_u32_e32 v16, vcc, s3, v76
	s_mov_b32 s3, 0x2d000
	s_nop 0
	v_addc_co_u32_e32 v17, vcc, 0, v77, vcc
	v_add_co_u32_e32 v2, vcc, s3, v2
	global_load_dwordx2 v[96:97], v[8:9], off
	global_load_dwordx2 v[100:101], v[12:13], off
	global_load_dwordx2 v[102:103], v[16:17], off
	v_addc_co_u32_e32 v3, vcc, 0, v3, vcc
	global_load_dword v140, v[6:7], off offset:-4096
	global_load_dword v142, v[6:7], off
	global_load_dword v144, v[10:11], off offset:-4096
	global_load_dword v149, v[10:11], off
	global_load_dword v156, v[14:15], off offset:-4096
	global_load_dword v157, v[14:15], off
	global_load_dword v158, v[2:3], off offset:-4096
	global_load_dword v159, v[2:3], off
	v_lshl_add_u64 v[2:3], v[4:5], 0, s[36:37]
	s_mov_b32 s9, s37
	v_ashrrev_i32_e32 v19, 4, v18
	v_lshl_add_u64 v[2:3], v[2:3], 0, s[8:9]
	s_mov_b64 s[8:9], 0x4000
	v_lshl_add_u64 v[84:85], v[2:3], 0, s[8:9]
	v_add_co_u32_e32 v2, vcc, s11, v2
	v_lshlrev_b32_e32 v88, 2, v19
	s_nop 0
	v_addc_co_u32_e32 v3, vcc, 0, v3, vcc
	v_ashrrev_i32_e32 v89, 31, v88
	v_readlane_b32 s8, v254, 47
	global_load_dwordx4 v[22:25], v[2:3], off
	global_load_dwordx2 v[92:93], v[76:77], off
	global_load_dwordx4 v[26:29], v[84:85], off offset:16
	v_lshl_add_u64 v[2:3], v[88:89], 2, s[6:7]
	s_lshl_b32 s6, s8, 2
	s_mov_b32 s7, s37
	v_lshl_add_u64 v[14:15], v[2:3], 0, s[6:7]
	global_load_dwordx4 v[2:5], v[14:15], off
	global_load_dwordx4 v[6:9], v[14:15], off offset:64
	global_load_dwordx4 v[10:13], v[14:15], off offset:128
	s_nop 0
	global_load_dwordx4 v[14:17], v[14:15], off offset:192
	v_add_u32_e32 v0, 0, v0
	s_movk_i32 s3, 0x11c
	v_mad_u64_u32 v[20:21], s[6:7], v18, s3, v[0:1]
	v_and_b32_e32 v124, 15, v18
	v_readlane_b32 s7, v254, 25
	v_lshlrev_b32_e32 v132, 3, v18
	v_and_b32_e32 v133, -16, v18
	v_readlane_b32 s3, v254, 43
	s_movk_i32 s11, 0x90
	v_cmp_gt_u32_e64 s[86:87], 16, v18
	v_lshl_add_u32 v135, v18, 2, s7
	v_or_b32_e32 v18, s10, v124
	v_or_b32_e32 v30, s3, v124
	v_mul_lo_u32 v18, v18, s11
	v_mul_lo_u32 v31, v30, s11
	s_add_i32 s3, 0, 0x15c00
	s_add_i32 s6, 0, 0x18000
	v_add_u32_e32 v34, 0, v18
	v_add_u32_e32 v18, s10, v88
	v_sub_u32_e32 v21, v124, v88
	v_add_u32_e32 v31, s3, v31
	s_add_i32 s3, 0, 0x11400
	v_lshlrev_b32_e32 v35, 2, v18
	v_lshl_add_u32 v36, v18, 1, s6
	v_or_b32_e32 v18, s8, v124
	v_add_u32_e32 v32, s3, v133
	v_cmp_gt_i32_e64 s[88:89], 0, v21
	v_cmp_gt_i32_e64 s[90:91], 1, v21
	v_cmp_gt_i32_e64 s[92:93], 2, v21
	v_cmp_gt_i32_e64 s[94:95], 3, v21
	v_mul_u32_u24_e32 v21, 0x90, v18
	v_mul_u32_u24_e32 v37, 0x110, v18
	v_mov_b32_e32 v18, s3
	v_readlane_b32 s3, v254, 44
	v_mul_lo_u32 v30, v30, s29
	v_mad_u32_u24 v137, v124, s11, v18
	v_or_b32_e32 v138, s3, v124
	v_readlane_b32 s3, v255, 9
	v_readlane_b32 s9, v254, 48
	v_add_u32_e32 v30, 0, v30
	v_add_u32_e32 v33, s6, v133
	v_readlane_b32 s7, v254, 24
	v_add_u32_e32 v38, 0x1200, v137
	v_add_u32_e32 v39, 0x2400, v137
	v_add_u32_e32 v40, 0x3600, v137
	v_add_u32_e32 v94, s8, v88
	v_mul_u32_u24_e32 v41, 0x110, v124
	v_lshl_add_u32 v139, v19, 3, s3
	v_readlane_b32 s3, v255, 10
	v_mov_b32_e32 v18, 0
	v_add_u32_e32 v19, 0, v35
	s_mov_b32 s2, 0
	v_add_u32_e32 v134, 0, v133
	v_lshl_add_u32 v136, v124, 2, s7
	v_ashrrev_i32_e32 v95, 31, v94
	v_lshl_add_u64 v[98:99], v[88:89], 0, s[8:9]
	v_add3_u32 v141, v41, v133, s3
	v_add_u32_e32 v143, s10, v20
	v_add_u32_e32 v145, v31, v133
	v_add_u32_e32 v146, v30, v133
	v_add_u32_e32 v147, v32, v21
	v_add_u32_e32 v148, v33, v37
	v_add_u32_e32 v150, v34, v133
	v_add_u32_e32 v151, 0x20800, v19
	v_add_u32_e32 v152, v38, v133
	v_add_u32_e32 v153, v39, v133
	v_add_u32_e32 v154, v40, v133
	v_add_u32_e32 v155, v36, v41
	v_mov_b32_e32 v19, v18
	v_mov_b32_e32 v20, v18
	v_mov_b32_e32 v21, v18
	v_mov_b32_e32 v30, v18
	v_mov_b32_e32 v31, v18
	v_mov_b32_e32 v32, v18
	v_mov_b32_e32 v33, v18
	v_mov_b32_e32 v34, v18
	v_mov_b32_e32 v35, v18
	v_mov_b32_e32 v36, v18
	v_mov_b32_e32 v37, v18
	v_mov_b32_e32 v38, v18
	v_mov_b32_e32 v39, v18
	v_mov_b32_e32 v40, v18
	v_mov_b32_e32 v41, v18
	v_mov_b32_e32 v42, v18
	v_mov_b32_e32 v43, v18
	v_mov_b32_e32 v44, v18
	v_mov_b32_e32 v45, v18
	v_mov_b32_e32 v50, v18
	v_mov_b32_e32 v51, v18
	v_mov_b32_e32 v52, v18
	v_mov_b32_e32 v53, v18
	v_mov_b32_e32 v46, v18
	v_mov_b32_e32 v47, v18
	v_mov_b32_e32 v48, v18
	v_mov_b32_e32 v49, v18
	v_mov_b32_e32 v54, v18
	v_mov_b32_e32 v55, v18
	v_mov_b32_e32 v56, v18
	v_mov_b32_e32 v57, v18
	s_waitcnt vmcnt(0)
	s_barrier
	s_branch .LBB0_1169
.LBB0_1168:
	s_or_b64 exec, exec, s[6:7]
	s_waitcnt lgkmcnt(0)
	ds_read_b128 v[114:117], v150 offset:52224
	ds_read_b128 v[118:121], v150 offset:52288
	v_add_u32_e32 v67, v137, v133
	ds_read_b128 v[160:163], v151
	ds_read_b128 v[164:167], v67
	ds_read_b128 v[168:171], v67 offset:2304
	ds_read_b128 v[172:175], v67 offset:64
	ds_read_b128 v[176:179], v67 offset:2368
	v_ashrrev_i32_e32 v67, 31, v66
	s_waitcnt lgkmcnt(4)
	v_pk_mul_f32 v[18:19], v[18:19], v[160:161]
	v_pk_mul_f32 v[20:21], v[20:21], v[162:163]
	v_pk_mul_f32 v[30:31], v[30:31], v[160:161]
	v_pk_mul_f32 v[32:33], v[32:33], v[162:163]
	s_waitcnt lgkmcnt(3)
	v_mfma_f32_16x16x32_bf16 v[18:21], v[114:117], v[164:167], v[18:21]
	s_waitcnt lgkmcnt(2)
	v_mfma_f32_16x16x32_bf16 v[30:33], v[114:117], v[168:171], v[30:33]
	s_waitcnt lgkmcnt(1)
	v_mfma_f32_16x16x32_bf16 v[18:21], v[118:121], v[172:175], v[18:21]
	s_waitcnt lgkmcnt(0)
	v_mfma_f32_16x16x32_bf16 v[30:33], v[118:121], v[176:179], v[30:33]
	ds_read_b128 v[164:167], v152
	ds_read_b128 v[168:171], v152 offset:2304
	ds_read_b128 v[172:175], v152 offset:64
	ds_read_b128 v[176:179], v152 offset:2368
	v_pk_mul_f32 v[34:35], v[34:35], v[160:161]
	v_pk_mul_f32 v[36:37], v[36:37], v[162:163]
	v_pk_mul_f32 v[38:39], v[38:39], v[160:161]
	v_pk_mul_f32 v[40:41], v[40:41], v[162:163]
	s_waitcnt lgkmcnt(3)
	v_mfma_f32_16x16x32_bf16 v[34:37], v[114:117], v[164:167], v[34:37]
	s_waitcnt lgkmcnt(2)
	v_mfma_f32_16x16x32_bf16 v[38:41], v[114:117], v[168:171], v[38:41]
	s_waitcnt lgkmcnt(1)
	v_mfma_f32_16x16x32_bf16 v[34:37], v[118:121], v[172:175], v[34:37]
	s_waitcnt lgkmcnt(0)
	v_mfma_f32_16x16x32_bf16 v[38:41], v[118:121], v[176:179], v[38:41]
	ds_read_b128 v[164:167], v153
	ds_read_b128 v[168:171], v153 offset:2304
	ds_read_b128 v[172:175], v153 offset:64
	ds_read_b128 v[176:179], v153 offset:2368
	v_pk_mul_f32 v[42:43], v[42:43], v[160:161]
	v_pk_mul_f32 v[44:45], v[44:45], v[162:163]
	v_pk_mul_f32 v[50:51], v[50:51], v[160:161]
	v_pk_mul_f32 v[52:53], v[52:53], v[162:163]
	s_waitcnt lgkmcnt(3)
	v_mfma_f32_16x16x32_bf16 v[42:45], v[114:117], v[164:167], v[42:45]
	s_waitcnt lgkmcnt(2)
	v_mfma_f32_16x16x32_bf16 v[50:53], v[114:117], v[168:171], v[50:53]
	s_waitcnt lgkmcnt(1)
	v_mfma_f32_16x16x32_bf16 v[42:45], v[118:121], v[172:175], v[42:45]
	s_waitcnt lgkmcnt(0)
	v_mfma_f32_16x16x32_bf16 v[50:53], v[118:121], v[176:179], v[50:53]
	ds_read_b128 v[164:167], v154
	ds_read_b128 v[168:171], v154 offset:2304
	ds_read_b128 v[172:175], v154 offset:64
	ds_read_b128 v[176:179], v154 offset:2368
	v_pk_mul_f32 v[46:47], v[46:47], v[160:161]
	v_pk_mul_f32 v[48:49], v[48:49], v[162:163]
	v_pk_mul_f32 v[54:55], v[54:55], v[160:161]
	v_pk_mul_f32 v[56:57], v[56:57], v[162:163]
	s_waitcnt lgkmcnt(3)
	v_mfma_f32_16x16x32_bf16 v[46:49], v[114:117], v[164:167], v[46:49]
	s_waitcnt lgkmcnt(0)
	s_barrier
	v_mfma_f32_16x16x32_bf16 v[54:57], v[114:117], v[168:171], v[54:57]
	ds_read2st64_b32 v[114:115], v136 offset1:1
	v_lshlrev_b64 v[66:67], 13, v[66:67]
	s_waitcnt vmcnt(3)
	v_lshlrev_b32_e32 v116, 16, v64
	v_and_b32_e32 v117, 0xffff0000, v64
	v_lshl_add_u64 v[66:67], s[4:5], 0, v[66:67]
	s_waitcnt lgkmcnt(0)
	v_add_f32_e32 v114, v114, v115
	v_fmamk_f32 v114, v114, 0x3c000000, v197
	v_cmp_gt_f32_e32 vcc, s81, v114
	v_mul_f32_e32 v115, 0x4b800000, v114
	v_lshl_add_u64 v[66:67], v[66:67], 0, s[36:37]
	v_cndmask_b32_e32 v114, v114, v115, vcc
	v_rsq_f32_e32 v114, v114
	s_mov_b64 s[6:7], 0x29401000
	v_lshl_add_u64 v[66:67], v[66:67], 0, s[6:7]
	v_mfma_f32_16x16x32_bf16 v[46:49], v[118:121], v[172:175], v[46:49]
	v_mul_f32_e32 v115, 0x45800000, v114
	v_cndmask_b32_e32 v114, v114, v115, vcc
	v_pk_mul_f32 v[70:71], v[70:71], v[114:115] op_sel_hi:[1,0]
	v_pk_mul_f32 v[68:69], v[68:69], v[114:115] op_sel_hi:[1,0]
	v_pk_mul_f32 v[70:71], v[2:3], v[70:71]
	v_pk_mul_f32 v[68:69], v[4:5], v[68:69]
	v_pk_mul_f32 v[70:71], v[70:71], v[116:117]
	v_mfma_f32_16x16x32_bf16 v[54:57], v[118:121], v[176:179], v[54:57]
	v_cvt_pk_bf16_f32 v64, v70, v71
	v_lshlrev_b32_e32 v70, 16, v65
	v_and_b32_e32 v71, 0xffff0000, v65
	v_pk_mul_f32 v[68:69], v[68:69], v[70:71]
	s_waitcnt vmcnt(2)
	v_lshlrev_b32_e32 v70, 16, v62
	v_cvt_pk_bf16_f32 v65, v68, v69
	v_lshl_add_u64 v[68:69], v[94:95], 1, v[66:67]
	global_store_dwordx2 v[68:69], v[64:65], off
	v_pk_mul_f32 v[64:65], v[104:105], v[114:115] op_sel_hi:[1,0]
	v_and_b32_e32 v71, 0xffff0000, v62
	v_pk_mul_f32 v[64:65], v[6:7], v[64:65]
	v_pk_mul_f32 v[68:69], v[72:73], v[114:115] op_sel_hi:[1,0]
	v_pk_mul_f32 v[64:65], v[64:65], v[70:71]
	v_pk_mul_f32 v[68:69], v[8:9], v[68:69]
	v_cvt_pk_bf16_f32 v62, v64, v65
	v_lshlrev_b32_e32 v64, 16, v63
	v_and_b32_e32 v65, 0xffff0000, v63
	v_pk_mul_f32 v[64:65], v[68:69], v[64:65]
	s_waitcnt vmcnt(2)
	v_lshlrev_b32_e32 v68, 16, v60
	v_cvt_pk_bf16_f32 v63, v64, v65
	v_lshl_add_u64 v[64:65], v[98:99], 1, v[66:67]
	global_store_dwordx2 v[64:65], v[62:63], off offset:32
	v_pk_mul_f32 v[62:63], v[108:109], v[114:115] op_sel_hi:[1,0]
	v_and_b32_e32 v69, 0xffff0000, v60
	v_pk_mul_f32 v[62:63], v[10:11], v[62:63]
	v_pk_mul_f32 v[66:67], v[106:107], v[114:115] op_sel_hi:[1,0]
	v_pk_mul_f32 v[62:63], v[62:63], v[68:69]
	v_pk_mul_f32 v[66:67], v[12:13], v[66:67]
	v_cvt_pk_bf16_f32 v60, v62, v63
	v_lshlrev_b32_e32 v62, 16, v61
	v_and_b32_e32 v63, 0xffff0000, v61
	v_pk_mul_f32 v[62:63], v[66:67], v[62:63]
	s_waitcnt vmcnt(2)
	v_lshlrev_b32_e32 v66, 16, v58
	v_cvt_pk_bf16_f32 v61, v62, v63
	global_store_dwordx2 v[64:65], v[60:61], off offset:64
	v_pk_mul_f32 v[60:61], v[112:113], v[114:115] op_sel_hi:[1,0]
	v_and_b32_e32 v67, 0xffff0000, v58
	v_pk_mul_f32 v[60:61], v[14:15], v[60:61]
	v_pk_mul_f32 v[62:63], v[110:111], v[114:115] op_sel_hi:[1,0]
	v_pk_mul_f32 v[60:61], v[60:61], v[66:67]
	v_pk_mul_f32 v[62:63], v[16:17], v[62:63]
	v_cvt_pk_bf16_f32 v58, v60, v61
	v_lshlrev_b32_e32 v60, 16, v59
	v_and_b32_e32 v61, 0xffff0000, v59
	v_pk_mul_f32 v[60:61], v[62:63], v[60:61]
	s_cmp_lg_u32 s3, 32
	v_cvt_pk_bf16_f32 v59, v60, v61
	global_store_dwordx2 v[64:65], v[58:59], off offset:96
	v_cvt_pk_bf16_f32 v58, v18, v19
	v_cvt_pk_bf16_f32 v59, v20, v21
	ds_write_b64 v155, v[58:59]
	v_cvt_pk_bf16_f32 v58, v30, v31
	v_cvt_pk_bf16_f32 v59, v32, v33
	ds_write_b64 v155, v[58:59] offset:4352
	v_cvt_pk_bf16_f32 v58, v34, v35
	v_cvt_pk_bf16_f32 v59, v36, v37
	ds_write_b64 v155, v[58:59] offset:8704
	v_cvt_pk_bf16_f32 v58, v38, v39
	v_cvt_pk_bf16_f32 v59, v40, v41
	ds_write_b64 v155, v[58:59] offset:13056
	v_cvt_pk_bf16_f32 v58, v42, v43
	v_cvt_pk_bf16_f32 v59, v44, v45
	ds_write_b64 v155, v[58:59] offset:17408
	v_cvt_pk_bf16_f32 v58, v50, v51
	v_cvt_pk_bf16_f32 v59, v52, v53
	ds_write_b64 v155, v[58:59] offset:21760
	v_cvt_pk_bf16_f32 v58, v46, v47
	v_cvt_pk_bf16_f32 v59, v48, v49
	ds_write_b64 v155, v[58:59] offset:26112
	v_cvt_pk_bf16_f32 v58, v54, v55
	v_cvt_pk_bf16_f32 v59, v56, v57
	s_mov_b32 s2, s3
	ds_write_b64 v155, v[58:59] offset:30464
	v_mov_b32_e32 v75, v214
	v_mov_b32_e32 v125, v215
	v_mov_b32_e32 v126, v216
	v_mov_b32_e32 v127, v217
	v_mov_b32_e32 v128, v218
	v_mov_b32_e32 v129, v219
	v_mov_b32_e32 v130, v220
	v_mov_b32_e32 v131, v221
	v_mov_b32_e32 v140, v222
	v_mov_b32_e32 v142, v223
	v_mov_b32_e32 v144, v224
	v_mov_b32_e32 v149, v225
	v_mov_b32_e32 v156, v226
	v_mov_b32_e32 v157, v227
	v_mov_b32_e32 v158, v228
	v_mov_b32_e32 v159, v229
	v_mov_b32_e32 v22, v230
	v_mov_b32_e32 v23, v231
	v_mov_b32_e32 v24, v232
	v_mov_b32_e32 v25, v233
	v_mov_b32_e32 v26, v234
	v_mov_b32_e32 v27, v235
	v_mov_b32_e32 v28, v236
	v_mov_b32_e32 v29, v237
	s_cbranch_scc0 .LBB0_1179
.LBB0_1169:
	v_pk_add_f32 v[118:119], v[92:93], 0 op_sel_hi:[1,0]
	v_pk_add_f32 v[116:117], v[118:119], v[80:81]
	v_pk_add_f32 v[114:115], v[116:117], v[82:83]
	v_pk_add_f32 v[112:113], v[114:115], v[86:87]
	v_pk_add_f32 v[110:111], v[112:113], v[90:91]
	v_pk_add_f32 v[108:109], v[110:111], v[96:97]
	v_pk_add_f32 v[106:107], v[108:109], v[100:101]
	s_nop 0
	v_pk_add_f32 v[104:105], v[106:107], v[102:103]
	s_add_i32 s3, s2, 1
	s_cmp_eq_u32 s2, 31
	s_cbranch_scc1 .Lhg_nopf
	s_lshl_b32 s6, s3, 6
	s_mov_b32 s7, s37
	s_lshl_b64 s[8:9], s[6:7], 13
	v_lshl_add_u64 v[238:239], v[76:77], 0, s[8:9]
	v_mad_u64_u32 v[240:241], s[8:9], s6, v204, v[78:79]
	s_or_b32 s8, s6, 1
	s_mov_b32 s9, s37
	v_add_co_u32_e32 v242, vcc, 0x1000, v240
	s_lshl_b64 s[10:11], s[8:9], 13
	s_nop 0
	v_addc_co_u32_e32 v243, vcc, 0, v241, vcc
	v_lshl_add_u64 v[244:245], v[76:77], 0, s[10:11]
	global_load_dwordx2 v[92:93], v[238:239], off
	global_load_dword v214, v[240:241], off
	global_load_dword v215, v[242:243], off
	global_load_dwordx2 v[80:81], v[244:245], off
	v_mad_u64_u32 v[238:239], s[8:9], s8, v204, v[78:79]
	v_add_co_u32_e32 v240, vcc, 0x1000, v238
	s_or_b32 s8, s6, 2
	s_mov_b32 s9, s37
	v_addc_co_u32_e32 v241, vcc, 0, v239, vcc
	s_lshl_b64 s[10:11], s[8:9], 13
	v_mad_u64_u32 v[244:245], s[8:9], s8, v204, v[78:79]
	v_add_co_u32_e32 v58, vcc, 0x1000, v244
	s_or_b32 s8, s6, 3
	s_mov_b32 s9, s37
	v_lshl_add_u64 v[242:243], v[76:77], 0, s[10:11]
	v_addc_co_u32_e32 v59, vcc, 0, v245, vcc
	global_load_dword v216, v[238:239], off
	global_load_dword v217, v[240:241], off
	global_load_dwordx2 v[82:83], v[242:243], off
	global_load_dword v218, v[244:245], off
	global_load_dword v219, v[58:59], off
	s_lshl_b64 s[10:11], s[8:9], 13
	v_mad_u64_u32 v[240:241], s[8:9], s8, v204, v[78:79]
	s_or_b32 s8, s6, 4
	s_mov_b32 s9, s37
	v_lshl_add_u64 v[238:239], v[76:77], 0, s[10:11]
	v_add_co_u32_e32 v242, vcc, 0x1000, v240
	s_lshl_b64 s[10:11], s[8:9], 13
	s_nop 0
	v_addc_co_u32_e32 v243, vcc, 0, v241, vcc
	v_lshl_add_u64 v[244:245], v[76:77], 0, s[10:11]
	global_load_dwordx2 v[86:87], v[238:239], off
	global_load_dword v220, v[240:241], off
	global_load_dword v221, v[242:243], off
	global_load_dwordx2 v[90:91], v[244:245], off
	v_mad_u64_u32 v[238:239], s[8:9], s8, v204, v[78:79]
	v_add_co_u32_e32 v240, vcc, 0x1000, v238
	s_or_b32 s8, s6, 5
	s_mov_b32 s9, s37
	v_addc_co_u32_e32 v241, vcc, 0, v239, vcc
	s_lshl_b64 s[10:11], s[8:9], 13
	v_mad_u64_u32 v[244:245], s[8:9], s8, v204, v[78:79]
	v_add_co_u32_e32 v58, vcc, 0x1000, v244
	s_or_b32 s8, s6, 6
	s_mov_b32 s9, s37
	v_lshl_add_u64 v[242:243], v[76:77], 0, s[10:11]
	v_addc_co_u32_e32 v59, vcc, 0, v245, vcc
	global_load_dword v222, v[238:239], off
	global_load_dword v223, v[240:241], off
	global_load_dwordx2 v[96:97], v[242:243], off
	global_load_dword v224, v[244:245], off
	global_load_dword v225, v[58:59], off
	s_lshl_b64 s[10:11], s[8:9], 13
	v_mad_u64_u32 v[240:241], s[8:9], s8, v204, v[78:79]
	s_or_b32 s6, s6, 7
	v_lshl_add_u64 v[238:239], v[76:77], 0, s[10:11]
	v_add_co_u32_e32 v242, vcc, 0x1000, v240
	s_lshl_b64 s[8:9], s[6:7], 13
	s_nop 0
	v_addc_co_u32_e32 v243, vcc, 0, v241, vcc
	v_lshl_add_u64 v[244:245], v[76:77], 0, s[8:9]
	global_load_dwordx2 v[100:101], v[238:239], off
	global_load_dword v226, v[240:241], off
	global_load_dword v227, v[242:243], off
	global_load_dwordx2 v[102:103], v[244:245], off
	v_mad_u64_u32 v[238:239], s[6:7], s6, v204, v[78:79]
	v_add_co_u32_e32 v240, vcc, 0x1000, v238
	s_mul_i32 s6, s3, 0x180000
	s_mov_b32 s7, s37
	v_addc_co_u32_e32 v241, vcc, 0, v239, vcc
	v_lshl_add_u64 v[242:243], v[84:85], 0, s[6:7]
	global_load_dword v228, v[238:239], off
	global_load_dword v229, v[240:241], off
	s_nop 0
	global_load_dwordx4 v[230:233], v[242:243], off
	s_nop 0
	global_load_dwordx4 v[234:237], v[242:243], off offset:16
.Lhg_nopf:
	v_add_u32_e32 v58, s18, v132
	v_add_u32_e32 v160, 0, v132
	v_readlane_b32 s6, v254, 20
	v_readlane_b32 s7, v254, 21
	s_nop 1
	s_andn2_b64 vcc, exec, s[6:7]
	s_mov_b64 s[6:7], -1
	ds_write_b64 v58, v[104:105]
	v_add_u32_e32 v58, 0x20a00, v160
	s_waitcnt lgkmcnt(0)
	s_barrier
	ds_read2st64_b64 v[70:73], v58 offset1:1
	ds_read2st64_b64 v[66:69], v58 offset0:2 offset1:3
	ds_read2st64_b64 v[62:65], v58 offset0:4 offset1:5
	ds_read2st64_b64 v[58:61], v58 offset0:6 offset1:7
	s_waitcnt lgkmcnt(3)
	v_pk_add_f32 v[122:123], v[70:71], 0 op_sel_hi:[1,0]
	s_nop 0
	v_pk_add_f32 v[70:71], v[122:123], v[72:73]
	s_waitcnt lgkmcnt(2)
	v_pk_add_f32 v[70:71], v[70:71], v[66:67]
	s_nop 0
	v_pk_add_f32 v[70:71], v[70:71], v[68:69]
	s_waitcnt lgkmcnt(1)
	v_pk_add_f32 v[120:121], v[70:71], v[62:63]
	s_nop 0
	v_pk_add_f32 v[120:121], v[120:121], v[64:65]
	s_waitcnt lgkmcnt(0)
	v_pk_add_f32 v[120:121], v[120:121], v[58:59]
	s_nop 0
	v_pk_add_f32 v[120:121], v[120:121], v[60:61]
	s_cbranch_vccnz .LBB0_1171
	s_mov_b64 s[6:7], 0

.LBB0_1173:
	v_readlane_b32 s6, v254, 18
	v_readlane_b32 s7, v254, 19
	s_mul_i32 s3, s20, 0x880
	s_nop 0
	v_cndmask_b32_e64 v123, v123, 0, s[6:7]
	v_cndmask_b32_e64 v122, v122, 0, s[6:7]
	v_readlane_b32 s6, v254, 26
	v_pk_add_f32 v[72:73], v[72:73], v[122:123]
	v_readlane_b32 s7, v254, 27
	s_nop 1
	v_cndmask_b32_e64 v73, v123, v73, s[6:7]
	v_cndmask_b32_e64 v72, v122, v72, s[6:7]
	v_readlane_b32 s6, v254, 28
	v_pk_add_f32 v[66:67], v[66:67], v[72:73]
	v_readlane_b32 s7, v254, 29
	s_nop 1
	v_cndmask_b32_e64 v67, v73, v67, s[6:7]
	v_cndmask_b32_e64 v66, v72, v66, s[6:7]
	v_readlane_b32 s6, v254, 30
	v_pk_add_f32 v[68:69], v[68:69], v[66:67]
	v_readlane_b32 s7, v254, 31
	s_nop 1
	v_cndmask_b32_e64 v67, v67, v69, s[6:7]
	v_cndmask_b32_e64 v66, v66, v68, s[6:7]
	v_readlane_b32 s6, v254, 32
	v_pk_add_f32 v[62:63], v[62:63], v[66:67]
	v_readlane_b32 s7, v254, 33
	v_and_b32_e32 v69, 0xffff0000, v125
	v_lshlrev_b32_e32 v68, 16, v125
	v_cndmask_b32_e64 v63, v67, v63, s[6:7]
	v_cndmask_b32_e64 v62, v66, v62, s[6:7]
	v_readlane_b32 s6, v254, 34
	v_pk_add_f32 v[64:65], v[64:65], v[62:63]
	v_readlane_b32 s7, v254, 35
	v_lshlrev_b32_e32 v66, 16, v75
	v_and_b32_e32 v67, 0xffff0000, v75
	v_cndmask_b32_e64 v63, v63, v65, s[6:7]
	v_cndmask_b32_e64 v62, v62, v64, s[6:7]
	v_readlane_b32 s6, v254, 36
	v_pk_add_f32 v[58:59], v[58:59], v[62:63]
	v_readlane_b32 s7, v254, 37
	s_nop 1
	v_cndmask_b32_e64 v59, v63, v59, s[6:7]
	v_cndmask_b32_e64 v58, v62, v58, s[6:7]
	v_readlane_b32 s6, v254, 40
	v_pk_add_f32 v[60:61], v[60:61], v[58:59]
	v_readlane_b32 s7, v254, 41
	s_nop 1
	v_cndmask_b32_e64 v58, v58, v60, s[6:7]
	v_sub_f32_e32 v60, v120, v70
	v_cndmask_b32_e64 v59, v59, v61, s[6:7]
	v_exp_f32_e32 v64, v60
	v_sub_f32_e32 v60, v121, v71
	v_exp_f32_e32 v65, v60
	v_pk_add_f32 v[60:61], v[118:119], v[58:59]
	s_nop 0
	v_pk_add_f32 v[62:63], v[60:61], v[70:71] neg_lo:[0,1] neg_hi:[0,1]
	v_exp_f32_e32 v60, v60
	v_min_f32_e32 v73, 0x42e60000, v63
	v_min_f32_e64 v63, -v63, s14
	v_min_f32_e32 v72, 0x42e60000, v62
	v_min_f32_e64 v62, -v62, s14
	v_exp_f32_e32 v63, v63
	v_exp_f32_e32 v72, v72
	v_exp_f32_e32 v73, v73
	v_exp_f32_e32 v62, v62
	v_exp_f32_e32 v61, v61
	v_mul_f32_e32 v63, v63, v69
	v_add_u32_e32 v69, s3, v0
	v_mul_f32_e32 v60, v60, v66
	v_mul_f32_e32 v72, v72, v66
	v_mul_f32_e32 v73, v73, v67
	v_mul_f32_e32 v62, v62, v68
	v_cvt_pk_bf16_f32 v68, v72, v73
	ds_write_b32 v69, v68
	v_mul_f32_e32 v61, v61, v67
	v_cvt_pk_bf16_f32 v60, v60, v61
	ds_write_b32 v69, v60 offset:17408
	v_cvt_pk_bf16_f32 v60, v62, v63
	ds_write_b32 v69, v60 offset:34816
	v_pk_add_f32 v[60:61], v[116:117], v[58:59]
	v_mul_f32_e32 v66, v64, v62
	v_mul_f32_e32 v67, v63, v65
	v_pk_add_f32 v[62:63], v[60:61], v[70:71] neg_lo:[0,1] neg_hi:[0,1]
	v_exp_f32_e32 v60, v60
	v_min_f32_e32 v117, 0x42e60000, v62
	v_min_f32_e32 v118, 0x42e60000, v63
	v_min_f32_e64 v62, -v62, s14
	v_exp_f32_e32 v117, v117
	v_exp_f32_e32 v118, v118
	v_exp_f32_e32 v62, v62
	v_min_f32_e64 v63, -v63, s14
	v_exp_f32_e32 v61, v61
	v_exp_f32_e32 v63, v63
	v_lshlrev_b32_e32 v68, 16, v126
	v_and_b32_e32 v72, 0xffff0000, v126
	v_lshlrev_b32_e32 v73, 16, v127
	v_mul_f32_e32 v60, v60, v68
	v_and_b32_e32 v116, 0xffff0000, v127
	v_mul_f32_e32 v117, v117, v68
	v_mul_f32_e32 v118, v118, v72
	v_mul_f32_e32 v62, v62, v73
	v_cvt_pk_bf16_f32 v73, v117, v118
	ds_write_b32 v69, v73 offset:272
	v_mul_f32_e32 v61, v61, v72
	v_cvt_pk_bf16_f32 v60, v60, v61
	v_mul_f32_e32 v63, v63, v116
	ds_write_b32 v69, v60 offset:17680
	v_cvt_pk_bf16_f32 v60, v62, v63
	ds_write_b32 v69, v60 offset:35088
	v_pk_add_f32 v[60:61], v[114:115], v[58:59]
	v_mul_f32_e32 v68, v64, v62
	v_mul_f32_e32 v72, v63, v65
	v_pk_add_f32 v[62:63], v[60:61], v[70:71] neg_lo:[0,1] neg_hi:[0,1]
	v_exp_f32_e32 v60, v60
	v_min_f32_e32 v117, 0x42e60000, v62
	v_min_f32_e32 v118, 0x42e60000, v63
	v_min_f32_e64 v62, -v62, s14
	v_exp_f32_e32 v117, v117
	v_exp_f32_e32 v118, v118
	v_exp_f32_e32 v62, v62
	v_min_f32_e64 v63, -v63, s14
	v_exp_f32_e32 v61, v61
	v_exp_f32_e32 v63, v63
	v_lshlrev_b32_e32 v73, 16, v128
	v_and_b32_e32 v114, 0xffff0000, v128
	v_lshlrev_b32_e32 v115, 16, v129
	v_mul_f32_e32 v60, v60, v73
	v_and_b32_e32 v116, 0xffff0000, v129
	v_mul_f32_e32 v117, v117, v73
	v_mul_f32_e32 v118, v118, v114
	v_mul_f32_e32 v62, v62, v115
	v_cvt_pk_bf16_f32 v115, v117, v118
	ds_write_b32 v69, v115 offset:544
	v_mul_f32_e32 v61, v61, v114
	v_cvt_pk_bf16_f32 v60, v60, v61
	v_mul_f32_e32 v63, v63, v116
	ds_write_b32 v69, v60 offset:17952
	v_cvt_pk_bf16_f32 v60, v62, v63
	ds_write_b32 v69, v60 offset:35360
	v_pk_add_f32 v[60:61], v[112:113], v[58:59]
	v_mul_f32_e32 v73, v64, v62
	v_mul_f32_e32 v114, v63, v65
	v_pk_add_f32 v[62:63], v[60:61], v[70:71] neg_lo:[0,1] neg_hi:[0,1]
	v_exp_f32_e32 v60, v60
	v_min_f32_e32 v117, 0x42e60000, v62
	v_min_f32_e32 v118, 0x42e60000, v63
	v_min_f32_e64 v62, -v62, s14
	v_exp_f32_e32 v117, v117
	v_exp_f32_e32 v118, v118
	v_exp_f32_e32 v62, v62
	v_min_f32_e64 v63, -v63, s14
	v_exp_f32_e32 v61, v61
	v_exp_f32_e32 v63, v63
	v_lshlrev_b32_e32 v112, 16, v130
	v_and_b32_e32 v113, 0xffff0000, v130
	v_lshlrev_b32_e32 v115, 16, v131
	v_mul_f32_e32 v60, v60, v112
	v_and_b32_e32 v116, 0xffff0000, v131
	v_mul_f32_e32 v117, v117, v112
	v_mul_f32_e32 v118, v118, v113
	v_mul_f32_e32 v62, v62, v115
	v_cvt_pk_bf16_f32 v115, v117, v118
	ds_write_b32 v69, v115 offset:816
	v_mul_f32_e32 v61, v61, v113
	v_cvt_pk_bf16_f32 v60, v60, v61
	v_mul_f32_e32 v63, v63, v116
	ds_write_b32 v69, v60 offset:18224
	v_cvt_pk_bf16_f32 v60, v62, v63
	ds_write_b32 v69, v60 offset:35632
	v_pk_add_f32 v[60:61], v[110:111], v[58:59]
	v_mul_f32_e32 v112, v64, v62
	v_mul_f32_e32 v113, v63, v65
	v_pk_add_f32 v[62:63], v[60:61], v[70:71] neg_lo:[0,1] neg_hi:[0,1]
	v_exp_f32_e32 v60, v60
	v_min_f32_e32 v117, 0x42e60000, v62
	v_min_f32_e32 v118, 0x42e60000, v63
	v_min_f32_e64 v62, -v62, s14
	v_exp_f32_e32 v117, v117
	v_exp_f32_e32 v118, v118
	v_exp_f32_e32 v62, v62
	v_min_f32_e64 v63, -v63, s14
	v_exp_f32_e32 v61, v61
	v_exp_f32_e32 v63, v63
	v_lshlrev_b32_e32 v110, 16, v140
	v_and_b32_e32 v111, 0xffff0000, v140
	v_lshlrev_b32_e32 v115, 16, v142
	v_mul_f32_e32 v60, v60, v110
	v_and_b32_e32 v116, 0xffff0000, v142
	v_mul_f32_e32 v117, v117, v110
	v_mul_f32_e32 v118, v118, v111
	v_mul_f32_e32 v62, v62, v115
	v_cvt_pk_bf16_f32 v115, v117, v118
	ds_write_b32 v69, v115 offset:1088
	v_mul_f32_e32 v61, v61, v111
	v_cvt_pk_bf16_f32 v60, v60, v61
	v_mul_f32_e32 v63, v63, v116
	ds_write_b32 v69, v60 offset:18496
	v_cvt_pk_bf16_f32 v60, v62, v63
	ds_write_b32 v69, v60 offset:35904
	v_pk_add_f32 v[60:61], v[108:109], v[58:59]
	v_mul_f32_e32 v110, v64, v62
	v_mul_f32_e32 v111, v63, v65
	v_pk_add_f32 v[62:63], v[60:61], v[70:71] neg_lo:[0,1] neg_hi:[0,1]
	v_exp_f32_e32 v60, v60
	v_min_f32_e32 v117, 0x42e60000, v62
	v_min_f32_e32 v118, 0x42e60000, v63
	v_min_f32_e64 v62, -v62, s14
	v_exp_f32_e32 v117, v117
	v_exp_f32_e32 v118, v118
	v_exp_f32_e32 v62, v62
	v_min_f32_e64 v63, -v63, s14
	v_exp_f32_e32 v61, v61
	v_exp_f32_e32 v63, v63
	v_lshlrev_b32_e32 v108, 16, v144
	v_and_b32_e32 v109, 0xffff0000, v144
	v_lshlrev_b32_e32 v115, 16, v149
	v_mul_f32_e32 v60, v60, v108
	v_and_b32_e32 v116, 0xffff0000, v149
	v_mul_f32_e32 v117, v117, v108
	v_mul_f32_e32 v118, v118, v109
	v_mul_f32_e32 v62, v62, v115
	v_cvt_pk_bf16_f32 v115, v117, v118
	ds_write_b32 v69, v115 offset:1360
	v_mul_f32_e32 v61, v61, v109
	v_cvt_pk_bf16_f32 v60, v60, v61
	v_mul_f32_e32 v63, v63, v116
	ds_write_b32 v69, v60 offset:18768
	v_cvt_pk_bf16_f32 v60, v62, v63
	ds_write_b32 v69, v60 offset:36176
	v_pk_add_f32 v[60:61], v[106:107], v[58:59]
	v_mul_f32_e32 v108, v64, v62
	v_mul_f32_e32 v109, v63, v65
	v_pk_add_f32 v[62:63], v[60:61], v[70:71] neg_lo:[0,1] neg_hi:[0,1]
	v_exp_f32_e32 v60, v60
	v_min_f32_e32 v117, 0x42e60000, v62
	v_min_f32_e32 v118, 0x42e60000, v63
	v_min_f32_e64 v62, -v62, s14
	v_exp_f32_e32 v117, v117
	v_exp_f32_e32 v118, v118
	v_exp_f32_e32 v62, v62
	v_min_f32_e64 v63, -v63, s14
	v_exp_f32_e32 v61, v61
	v_exp_f32_e32 v63, v63
	v_lshlrev_b32_e32 v106, 16, v156
	v_and_b32_e32 v107, 0xffff0000, v156
	v_lshlrev_b32_e32 v115, 16, v157
	v_mul_f32_e32 v60, v60, v106
	v_and_b32_e32 v116, 0xffff0000, v157
	v_mul_f32_e32 v117, v117, v106
	v_mul_f32_e32 v118, v118, v107
	v_mul_f32_e32 v62, v62, v115
	v_cvt_pk_bf16_f32 v115, v117, v118
	ds_write_b32 v69, v115 offset:1632
	v_mul_f32_e32 v61, v61, v107
	v_cvt_pk_bf16_f32 v60, v60, v61
	v_mul_f32_e32 v63, v63, v116
	ds_write_b32 v69, v60 offset:19040
	v_cvt_pk_bf16_f32 v60, v62, v63
	v_pk_add_f32 v[58:59], v[104:105], v[58:59]
	ds_write_b32 v69, v60 offset:36448
	v_pk_add_f32 v[60:61], v[58:59], v[70:71] neg_lo:[0,1] neg_hi:[0,1]
	v_exp_f32_e32 v58, v58
	v_min_f32_e32 v106, 0x42e60000, v60
	v_min_f32_e32 v107, 0x42e60000, v61
	v_min_f32_e64 v60, -v60, s14
	v_exp_f32_e32 v106, v106
	v_exp_f32_e32 v107, v107
	v_exp_f32_e32 v60, v60
	v_min_f32_e64 v61, -v61, s14
	v_exp_f32_e32 v59, v59
	v_exp_f32_e32 v61, v61
	v_lshlrev_b32_e32 v70, 16, v158
	v_and_b32_e32 v71, 0xffff0000, v158
	v_lshlrev_b32_e32 v104, 16, v159
	v_mul_f32_e32 v58, v58, v70
	v_and_b32_e32 v105, 0xffff0000, v159
	v_mul_f32_e32 v106, v106, v70
	v_mul_f32_e32 v107, v107, v71
	v_mul_f32_e32 v60, v60, v104
	v_cvt_pk_bf16_f32 v104, v106, v107
	ds_write_b32 v69, v104 offset:1904
	v_mul_f32_e32 v59, v59, v71
	v_cvt_pk_bf16_f32 v58, v58, v59
	v_mul_f32_e32 v61, v61, v105
	ds_write_b32 v69, v58 offset:19312
	v_cvt_pk_bf16_f32 v58, v60, v61
	ds_write_b32 v69, v58 offset:36720
	v_cvt_pk_bf16_f32 v58, v66, v68
	v_mul_f32_e32 v62, v64, v62
	v_mul_f32_e32 v63, v63, v65
	v_mul_f32_e32 v64, v64, v60
	v_mul_f32_e32 v65, v61, v65
	v_cvt_pk_bf16_f32 v59, v73, v112
	v_cvt_pk_bf16_f32 v60, v110, v108
	v_cvt_pk_bf16_f32 v61, v62, v64
	ds_write_b128 v143, v[58:61] offset:52224
	v_cvt_pk_bf16_f32 v58, v67, v72
	s_add_i32 s3, s2, 1
	v_cvt_pk_bf16_f32 v59, v114, v113
	v_cvt_pk_bf16_f32 v60, v111, v109
	v_cvt_pk_bf16_f32 v61, v63, v65
	ds_write_b128 v143, v[58:61] offset:52368
	v_add_u32_e32 v58, s19, v74
	s_cmp_eq_u32 s2, 31
	ds_write_b16 v58, v22
	ds_write_b16_d16_hi v58, v22 offset:144
	ds_write_b16 v58, v23 offset:288
	ds_write_b16_d16_hi v58, v23 offset:432
	ds_write_b16 v58, v24 offset:576
	ds_write_b16_d16_hi v58, v24 offset:720
	ds_write_b16 v58, v25 offset:864
	ds_write_b16_d16_hi v58, v25 offset:1008
	ds_write_b16 v58, v26 offset:1152
	ds_write_b16_d16_hi v58, v26 offset:1296
	ds_write_b16 v58, v27 offset:1440
	ds_write_b16_d16_hi v58, v27 offset:1584
	ds_write_b16 v58, v28 offset:1728
	ds_write_b16_d16_hi v58, v28 offset:1872
	ds_write_b16 v58, v29 offset:2016
	ds_write_b16_d16_hi v58, v29 offset:2160
